# attention loop: next-tile LDS stores interleaved into the PV MFMA run; K-fragment LDS reads issued before the prefetch loads at the loop top
# speedup vs baseline: 1.0281x; 1.0040x over previous
; DEV void attn_tile(const Params& p, int l, int tile, char* smem, bool do_store = true) {
;     ...
;     bf16x8 pb0[2], pb1[2];
;     {
;       float pe[16];
; #pragma unroll
;       for (int e = 0; e < 16; ++e) { pe[e] = __builtin_amdgcn_exp2f(s0[e] - m); lsum += pe[e]; }
; #pragma unroll
;       for (int k2 = 0; k2 < 2; ++k2) {
;         u32x4 u;
;         u[0] = pk2(pe[8 * k2 + 0], pe[8 * k2 + 1]); u[1] = pk2(pe[8 * k2 + 2], pe[8 * k2 + 3]);
;         u[2] = pk2(pe[8 * k2 + 4], pe[8 * k2 + 5]); u[3] = pk2(pe[8 * k2 + 6], pe[8 * k2 + 7]);
;         pb0[k2] = __builtin_bit_cast(bf16x8, u);
;       }
;     }
; #pragma unroll
;     for (int dt = 0; dt < 4; ++dt)
; #pragma unroll
;       for (int k2 = 0; k2 < 2; ++k2) o[dt] = __builtin_amdgcn_mfma_f32_32x32x16_bf16(vf[dt * 2 + k2], pb0[k2], o[dt], 0, 0, 0);
; #pragma unroll
;     for (int dt = 0; dt < 4; ++dt)
; #pragma unroll
;       for (int k2 = 0; k2 < 2; ++k2) vf[dt * 2 + k2] = *(const bf16x8*)(vp + dt * 32 * KROW + (32 + k2 * 16) * 2);
;     {
;       float pe[16];
; #pragma unroll
;       for (int e = 0; e < 16; ++e) { pe[e] = __builtin_amdgcn_exp2f(s1[e] - m); lsum += pe[e]; }
; #pragma unroll
;       for (int k2 = 0; k2 < 2; ++k2) {
;         u32x4 u;
;         u[0] = pk2(pe[8 * k2 + 0], pe[8 * k2 + 1]); u[1] = pk2(pe[8 * k2 + 2], pe[8 * k2 + 3]);
;         u[2] = pk2(pe[8 * k2 + 4], pe[8 * k2 + 5]); u[3] = pk2(pe[8 * k2 + 6], pe[8 * k2 + 7]);
;         pb1[k2] = __builtin_bit_cast(bf16x8, u);
;       }
;     }
; #pragma unroll
;     for (int dt = 0; dt < 4; ++dt)
; #pragma unroll
;       for (int k2 = 0; k2 < 2; ++k2) o[dt] = __builtin_amdgcn_mfma_f32_32x32x16_bf16(vf[dt * 2 + k2], pb1[k2], o[dt], 0, 0, 0);
;     }
;     if (kt + 1 < nkt) lstore(cur ^ 1);
.LBB0_599:
	v_sub_f32_e32 v80, v80, v208
	v_exp_f32_e32 v178, v80
	v_sub_f32_e32 v80, v81, v208
	v_exp_f32_e32 v179, v80
	v_sub_f32_e32 v80, v82, v208
	v_exp_f32_e32 v180, v80
	v_sub_f32_e32 v80, v83, v208
	v_exp_f32_e32 v181, v80
	v_sub_f32_e32 v80, v84, v208
	v_exp_f32_e32 v210, v80
	v_sub_f32_e32 v80, v85, v208
	v_exp_f32_e32 v211, v80
	v_sub_f32_e32 v80, v86, v208
	v_exp_f32_e32 v212, v80
	v_sub_f32_e32 v80, v87, v208
	v_exp_f32_e32 v213, v80
	v_sub_f32_e32 v80, v88, v208
	v_exp_f32_e32 v88, v80
	v_sub_f32_e32 v80, v89, v208
	v_exp_f32_e32 v89, v80
	v_sub_f32_e32 v80, v90, v208
	v_exp_f32_e32 v90, v80
	v_sub_f32_e32 v80, v91, v208
	v_exp_f32_e32 v91, v80
	v_sub_f32_e32 v80, v92, v208
	v_exp_f32_e32 v92, v80
	v_sub_f32_e32 v80, v93, v208
	v_exp_f32_e32 v93, v80
	v_sub_f32_e32 v80, v94, v208
	v_exp_f32_e32 v94, v80
	v_sub_f32_e32 v80, v95, v208
	v_exp_f32_e32 v214, v80
	v_cvt_pk_bf16_f32 v80, v178, v179
	v_cvt_pk_bf16_f32 v81, v180, v181
	v_cvt_pk_bf16_f32 v82, v210, v211
	v_cvt_pk_bf16_f32 v83, v212, v213
	v_add_f32_e32 v95, v178, v209
	v_add_f32_e32 v95, v179, v95
	s_waitcnt lgkmcnt(5)
	v_mfma_f32_32x32x16_bf16 v[32:47], v[166:169], v[80:83], v[32:47]
	v_add_f32_e32 v95, v180, v95
	v_add_f32_e32 v95, v181, v95
	v_add_f32_e32 v95, v210, v95
	v_cvt_pk_bf16_f32 v84, v88, v89
	v_cvt_pk_bf16_f32 v85, v90, v91
	v_cvt_pk_bf16_f32 v86, v92, v93
	v_cvt_pk_bf16_f32 v87, v94, v214
	v_mfma_f32_32x32x16_bf16 v[48:63], v[174:177], v[80:83], v[48:63]
	v_add_f32_e32 v95, v211, v95
	v_sub_f32_e32 v64, v64, v208
	v_add_f32_e32 v95, v212, v95
	v_add_f32_e32 v95, v213, v95
	v_add_f32_e32 v88, v88, v95
	v_add_f32_e32 v88, v89, v88
	v_add_f32_e32 v88, v90, v88
	s_waitcnt lgkmcnt(3)
	v_mfma_f32_32x32x16_bf16 v[16:31], v[146:149], v[80:83], v[16:31]
	v_add_f32_e32 v88, v91, v88
	v_add_f32_e32 v88, v92, v88
	v_add_f32_e32 v88, v93, v88
	v_add_f32_e32 v178, v94, v88
	s_xor_b32 s1, s1, 1
	s_mul_i32 s1, s1, 0x11000
	s_addk_i32 s31, 0x80
	s_waitcnt lgkmcnt(1)
	v_mfma_f32_32x32x16_bf16 v[0:15], v[154:157], v[80:83], v[0:15]
	s_mov_b64 s[38:39], 0x100
	s_add_i32 s0, s0, 1
	v_lshl_add_u64 v[186:187], v[186:187], 0, s[38:39]
	s_cmp_eq_u32 s36, s31
	v_mfma_f32_32x32x16_bf16 v[32:47], v[162:165], v[84:87], v[32:47]
	v_exp_f32_e32 v163, v64
	v_sub_f32_e32 v64, v65, v208
	v_exp_f32_e32 v164, v64
	v_sub_f32_e32 v64, v66, v208
	v_exp_f32_e32 v165, v64
	v_sub_f32_e32 v64, v67, v208
	v_exp_f32_e32 v166, v64
	v_sub_f32_e32 v64, v68, v208
	v_mfma_f32_32x32x16_bf16 v[48:63], v[170:173], v[84:87], v[48:63]
	v_exp_f32_e32 v167, v64
	v_sub_f32_e32 v64, v69, v208
	v_exp_f32_e32 v168, v64
	v_sub_f32_e32 v64, v70, v208
	v_exp_f32_e32 v169, v64
	v_sub_f32_e32 v64, v71, v208
	v_exp_f32_e32 v170, v64
	v_mfma_f32_32x32x16_bf16 v[16:31], v[150:153], v[84:87], v[16:31]
	v_sub_f32_e32 v64, v72, v208
	v_exp_f32_e32 v72, v64
	v_sub_f32_e32 v64, v73, v208
	v_exp_f32_e32 v73, v64
	v_sub_f32_e32 v64, v74, v208
	v_exp_f32_e32 v74, v64
	v_sub_f32_e32 v64, v75, v208
	s_waitcnt lgkmcnt(0)
	v_mfma_f32_32x32x16_bf16 v[0:15], v[158:161], v[84:87], v[0:15]
	ds_read_b128 v[150:153], v205 offset:35008
	ds_read_b128 v[154:157], v205 offset:35040
	ds_read_b128 v[158:161], v205 offset:43712
	ds_read_b128 v[146:149], v205 offset:43744
	ds_read_b128 v[92:95], v205 offset:52416
	ds_read_b128 v[88:91], v205 offset:52448
	ds_read_b128 v[84:87], v205 offset:61120
	ds_read_b128 v[80:83], v205 offset:61152
	v_add_f32_e32 v162, v214, v178
	v_exp_f32_e32 v75, v64
	v_sub_f32_e32 v64, v76, v208
	v_cvt_pk_bf16_f32 v68, v163, v164
	v_cvt_pk_bf16_f32 v69, v165, v166
	v_cvt_pk_bf16_f32 v70, v167, v168
	v_cvt_pk_bf16_f32 v71, v169, v170
	v_exp_f32_e32 v76, v64
	v_sub_f32_e32 v64, v77, v208
	v_add_f32_e32 v162, v163, v162
	s_waitcnt lgkmcnt(7)
	v_mfma_f32_32x32x16_bf16 v[48:63], v[150:153], v[68:71], v[48:63]
	v_add_u32_e32 v206, s1, v202
	s_waitcnt vmcnt(7)
	ds_write_b128 v206, v[114:117]
	s_waitcnt vmcnt(6)
	ds_write_b128 v206, v[118:121] offset:34816
	v_exp_f32_e32 v77, v64
	v_sub_f32_e32 v64, v78, v208
	v_add_f32_e32 v162, v164, v162
	v_exp_f32_e32 v78, v64
	v_sub_f32_e32 v64, v79, v208
	v_add_f32_e32 v162, v165, v162
	v_exp_f32_e32 v79, v64
	s_waitcnt lgkmcnt(7)
	v_mfma_f32_32x32x16_bf16 v[32:47], v[158:161], v[68:71], v[32:47]
	s_waitcnt vmcnt(5)
	ds_write_b128 v206, v[122:125] offset:8704
	s_waitcnt vmcnt(4)
	ds_write_b128 v206, v[126:129] offset:43520
	v_add_f32_e32 v162, v166, v162
	v_add_f32_e32 v162, v167, v162
	v_add_f32_e32 v162, v168, v162
	v_add_f32_e32 v162, v169, v162
	v_cvt_pk_bf16_f32 v64, v72, v73
	v_cvt_pk_bf16_f32 v65, v74, v75
	v_cvt_pk_bf16_f32 v66, v76, v77
	s_waitcnt lgkmcnt(7)
	v_mfma_f32_32x32x16_bf16 v[16:31], v[92:95], v[68:71], v[16:31]
	s_waitcnt vmcnt(3)
	ds_write_b128 v206, v[130:133] offset:17408
	s_waitcnt vmcnt(2)
	ds_write_b128 v206, v[134:137] offset:52224
	v_cvt_pk_bf16_f32 v67, v78, v79
	v_add_f32_e32 v162, v170, v162
	v_add_f32_e32 v72, v72, v162
	v_add_f32_e32 v72, v73, v72
	v_add_f32_e32 v72, v74, v72
	v_add_f32_e32 v72, v75, v72
	v_add_f32_e32 v72, v76, v72
	s_waitcnt lgkmcnt(7)
	v_mfma_f32_32x32x16_bf16 v[0:15], v[84:87], v[68:71], v[0:15]
	s_waitcnt vmcnt(1)
	ds_write_b128 v206, v[138:141] offset:26112
	s_waitcnt vmcnt(0)
	ds_write_b128 v206, v[142:145] offset:60928
	v_add_f32_e32 v72, v77, v72
	v_add_f32_e32 v72, v78, v72
	v_add_f32_e32 v209, v79, v72
	v_mfma_f32_32x32x16_bf16 v[48:63], v[154:157], v[64:67], v[48:63]
	v_mfma_f32_32x32x16_bf16 v[32:47], v[146:149], v[64:67], v[32:47]
	v_mfma_f32_32x32x16_bf16 v[16:31], v[88:91], v[64:67], v[16:31]
	s_waitcnt lgkmcnt(8)
	v_mfma_f32_32x32x16_bf16 v[0:15], v[80:83], v[64:67], v[0:15]
	s_waitcnt lgkmcnt(0)
	s_barrier
	s_cbranch_scc1 .LBB0_604

; DEV void attn_tile(const Params& p, int l, int tile, char* smem, bool do_store = true) {
;     ...
;   auto gload = [&](int kt) {
;     const int k0 = kt * 128;
; #pragma unroll
;     for (int i = 0; i < 4; ++i) {
;       const int kidx = k0 + kr0 + 32 * i;
;       const int krow = kidx < CTXL ? T_LAT + b * CTXL + kidx : b * SEQ + kidx - CTXL;
;       kreg[i] = *(const u32x4*)(ZK + (size_t)krow * 512 + head * 128 + kch * 8);
;       vreg[i] = *(const u32x4*)(vtb + (size_t)(vr0 + 32 * i) * TK + k0 + vch * 8);
;     }
;   };
;     ...
;     const char* Ks = smem + cur * ATT2_ST;
;     const char* Vs = Ks + 128 * KROW;
; #pragma unroll
;     for (int h2 = 0; h2 < 2; ++h2) {
;     const char* kp = Ks + (h2 * 64 + kos) * KROW + (map * 64 + hh * 8) * 2;
;     const char* vp = Vs + ql * KROW + hh * 16 + h2 * 128;
;     bf16x8 kf0[4], kf1[4];
; #pragma unroll
;     for (int ks = 0; ks < 4; ++ks) { kf0[ks] = *(const bf16x8*)(kp + ks * 32); kf1[ks] = *(const bf16x8*)(kp + 32 * KROW + ks * 32); }
.Latt_a3_inc:
	s_and_b32 s1, s0, 1
	s_mul_i32 s37, s1, 0x11000
	v_add_u32_e32 v64, s37, v204
	v_add_u32_e32 v65, s37, v201
	v_add_u32_e32 v210, v64, v203
	v_add_u32_e32 v205, v65, v96
	ds_read_b128 v[64:67], v210 offset:8704
	ds_read_b128 v[68:71], v210
	ds_read_b128 v[72:75], v210 offset:32
	ds_read_b128 v[212:215], v210 offset:8736
	ds_read_b128 v[76:79], v210 offset:64
	ds_read_b128 v[216:219], v210 offset:8768
	ds_read_b128 v[146:149], v210 offset:96
	ds_read_b128 v[178:181], v210 offset:8800
	s_mov_b32 s100, 0x20000
	s_mov_b32 s101, 0
	s_cmp_lg_u32 s0, 1
	s_cbranch_scc1 .Latt_a3_nd
	s_mul_i32 s100, s30, 0xf00
	s_sub_u32 s100, s100, 0x8080
	s_lshl_b32 s100, s100, 10
	s_mov_b32 s101, -1
.Latt_a3_nd:
	s_mov_b64 s[38:39], 0x100
	v_lshl_add_u64 v[220:221], v[220:221], 0, s[100:101]
	v_lshl_add_u64 v[222:223], v[222:223], 0, s[100:101]
	v_lshl_add_u64 v[224:225], v[224:225], 0, s[100:101]
	v_lshl_add_u64 v[228:229], v[228:229], 0, s[100:101]
	v_lshl_add_u64 v[230:231], v[230:231], 0, s[38:39]
	v_lshl_add_u64 v[238:239], v[238:239], 0, s[38:39]
	v_lshl_add_u64 v[242:243], v[242:243], 0, s[38:39]
	global_load_dwordx4 v[114:117], v[220:221], off
	global_load_dwordx4 v[118:121], v[186:187], off
	global_load_dwordx4 v[122:125], v[222:223], off
	global_load_dwordx4 v[126:129], v[230:231], off
	global_load_dwordx4 v[130:133], v[224:225], off
	global_load_dwordx4 v[134:137], v[238:239], off
	global_load_dwordx4 v[138:141], v[228:229], off
	global_load_dwordx4 v[142:145], v[242:243], off
	s_branch .Latt_a3_qk

; DEV void attn_tile(const Params& p, int l, int tile, char* smem, bool do_store = true) {
;     ...
;     for (int ks = 0; ks < 4; ++ks) { kf0[ks] = *(const bf16x8*)(kp + ks * 32); kf1[ks] = *(const bf16x8*)(kp + 32 * KROW + ks * 32); }
;     f32x16 s0, s1;
; #pragma unroll
;     for (int e = 0; e < 16; ++e) { s0[e] = 0.f; s1[e] = 0.f; }
; #pragma unroll
;     for (int ks = 0; ks < 4; ++ks) s0 = __builtin_amdgcn_mfma_f32_32x32x16_bf16(kf0[ks], qf[ks], s0, 0, 0, 0);
; #pragma unroll
;     for (int ks = 0; ks < 4; ++ks) s1 = __builtin_amdgcn_mfma_f32_32x32x16_bf16(kf1[ks], qf[ks], s1, 0, 0, 0);
;     bf16x8 vf[8];
; #pragma unroll
;     for (int dt = 0; dt < 4; ++dt)
; #pragma unroll
;       for (int k2 = 0; k2 < 2; ++k2) vf[dt * 2 + k2] = *(const bf16x8*)(vp + dt * 32 * KROW + (k2 * 16) * 2);
;     float mx = fmaxf(s0[0], s1[0]);
; #pragma unroll
;     for (int e = 1; e < 16; ++e) mx = fmaxf(mx, fmaxf(s0[e], s1[e]));
;     mx = xor32_max(mx);
;     const float mnew = (mx > m + 8.f) ? mx : m;
;     if (__any(mnew > m)) {
;       const float alpha = __builtin_amdgcn_exp2f(m - mnew);
;       lsum *= alpha;
; #pragma unroll
;       for (int dt = 0; dt < 4; ++dt)
; #pragma unroll
;         for (int e = 0; e < 16; ++e) o[dt][e] *= alpha;
;     }
;     m = mnew;
.Latt_a3_qk:
	s_waitcnt lgkmcnt(6)
	v_mfma_f32_32x32x16_bf16 v[80:95], v[68:71], v[110:113], 0
	s_waitcnt lgkmcnt(5)
	v_mfma_f32_32x32x16_bf16 v[80:95], v[72:75], v[106:109], v[80:95]
	s_waitcnt lgkmcnt(3)
	v_mfma_f32_32x32x16_bf16 v[80:95], v[76:79], v[102:105], v[80:95]
	v_mfma_f32_32x32x16_bf16 v[64:79], v[64:67], v[110:113], 0
	v_mfma_f32_32x32x16_bf16 v[64:79], v[212:215], v[106:109], v[64:79]
	s_waitcnt lgkmcnt(2)
	v_mfma_f32_32x32x16_bf16 v[64:79], v[216:219], v[102:105], v[64:79]
	s_waitcnt lgkmcnt(1)
	v_mfma_f32_32x32x16_bf16 v[80:95], v[146:149], v[98:101], v[80:95]
	ds_read_b128 v[174:177], v205 offset:34816
	ds_read_b128 v[170:173], v205 offset:34848
	ds_read_b128 v[166:169], v205 offset:43520
	ds_read_b128 v[162:165], v205 offset:43552
	ds_read_b128 v[146:149], v205 offset:52224
	ds_read_b128 v[150:153], v205 offset:52256
	ds_read_b128 v[154:157], v205 offset:60928
	ds_read_b128 v[158:161], v205 offset:60960
	s_waitcnt lgkmcnt(8)
	v_mfma_f32_32x32x16_bf16 v[64:79], v[178:181], v[98:101], v[64:79]
	s_nop 1
	v_max3_f32 v178, v80, v81, v82
	v_max3_f32 v179, v83, v84, v85
	v_max3_f32 v180, v86, v87, v88
	v_max3_f32 v181, v89, v90, v91
	v_max3_f32 v178, v178, v92, v93
	v_max3_f32 v179, v179, v94, v95
	s_nop 3
	v_max3_f32 v180, v180, v64, v65
	v_max3_f32 v181, v181, v66, v67
	v_max3_f32 v178, v178, v68, v69
	v_max3_f32 v179, v179, v70, v71
	v_max3_f32 v180, v180, v72, v73
	v_max3_f32 v181, v181, v74, v75
	v_max3_f32 v178, v178, v76, v77
	v_max3_f32 v179, v179, v78, v79
	v_max3_f32 v178, v178, v179, v180
	v_max_f32_e32 v178, v178, v181
	v_mov_b32_e32 v179, v178
	s_nop 1
	v_permlane32_swap_b32_e32 v178, v179
	v_max_f32_e32 v178, v178, v179
	v_add_f32_e32 v179, 0x41000000, v208
	v_cmp_gt_f32_e32 vcc, v178, v179
	s_nop 1
	v_cndmask_b32_e32 v211, v208, v178, vcc
	v_cmp_gt_f32_e32 vcc, v211, v208
	s_cbranch_vccz .LBB0_602
	v_sub_f32_e32 v178, v208, v211
	v_exp_f32_e32 v178, v178
	s_nop 0
	v_pk_mul_f32 v[62:63], v[62:63], v[178:179] op_sel_hi:[1,0]
	v_pk_mul_f32 v[60:61], v[60:61], v[178:179] op_sel_hi:[1,0]
	v_pk_mul_f32 v[58:59], v[58:59], v[178:179] op_sel_hi:[1,0]
	v_pk_mul_f32 v[56:57], v[56:57], v[178:179] op_sel_hi:[1,0]
	v_pk_mul_f32 v[54:55], v[54:55], v[178:179] op_sel_hi:[1,0]
	v_pk_mul_f32 v[52:53], v[52:53], v[178:179] op_sel_hi:[1,0]
	v_pk_mul_f32 v[50:51], v[50:51], v[178:179] op_sel_hi:[1,0]
	v_pk_mul_f32 v[48:49], v[48:49], v[178:179] op_sel_hi:[1,0]
	v_pk_mul_f32 v[46:47], v[46:47], v[178:179] op_sel_hi:[1,0]
	v_pk_mul_f32 v[44:45], v[44:45], v[178:179] op_sel_hi:[1,0]
	v_pk_mul_f32 v[42:43], v[42:43], v[178:179] op_sel_hi:[1,0]
	v_pk_mul_f32 v[40:41], v[40:41], v[178:179] op_sel_hi:[1,0]
	v_pk_mul_f32 v[38:39], v[38:39], v[178:179] op_sel_hi:[1,0]
	v_pk_mul_f32 v[36:37], v[36:37], v[178:179] op_sel_hi:[1,0]
	v_pk_mul_f32 v[34:35], v[34:35], v[178:179] op_sel_hi:[1,0]
	v_pk_mul_f32 v[32:33], v[32:33], v[178:179] op_sel_hi:[1,0]
	v_pk_mul_f32 v[30:31], v[30:31], v[178:179] op_sel_hi:[1,0]
	v_pk_mul_f32 v[28:29], v[28:29], v[178:179] op_sel_hi:[1,0]
	v_pk_mul_f32 v[26:27], v[26:27], v[178:179] op_sel_hi:[1,0]
	v_pk_mul_f32 v[24:25], v[24:25], v[178:179] op_sel_hi:[1,0]
	v_pk_mul_f32 v[22:23], v[22:23], v[178:179] op_sel_hi:[1,0]
	v_pk_mul_f32 v[20:21], v[20:21], v[178:179] op_sel_hi:[1,0]
	v_pk_mul_f32 v[18:19], v[18:19], v[178:179] op_sel_hi:[1,0]
	v_pk_mul_f32 v[16:17], v[16:17], v[178:179] op_sel_hi:[1,0]
	v_pk_mul_f32 v[14:15], v[14:15], v[178:179] op_sel_hi:[1,0]
	v_pk_mul_f32 v[12:13], v[12:13], v[178:179] op_sel_hi:[1,0]
	v_pk_mul_f32 v[10:11], v[10:11], v[178:179] op_sel_hi:[1,0]
	v_pk_mul_f32 v[8:9], v[8:9], v[178:179] op_sel_hi:[1,0]
	v_pk_mul_f32 v[6:7], v[6:7], v[178:179] op_sel_hi:[1,0]
	v_pk_mul_f32 v[4:5], v[4:5], v[178:179] op_sel_hi:[1,0]
	v_pk_mul_f32 v[2:3], v[2:3], v[178:179] op_sel_hi:[1,0]
	v_pk_mul_f32 v[0:1], v[0:1], v[178:179] op_sel_hi:[1,0]
	v_mul_f32_e32 v209, v209, v178
